# GU K-loop: LDS-DMA addresses in SGPR-base + lane-offset (saddr) form, no per-DMA 64-bit VALU add in the load segments
# speedup vs baseline: 1.0036x; 1.0028x over previous
; #define PG8_STAGE(bufoff, gbase, voff) do { _Pragma("unroll") for (int _i = 0; _i < 2; ++_i) \
;         __builtin_amdgcn_global_load_lds((const unsigned*)((const char*)(gbase) + (voff)[_i]), (PG8_LAS unsigned*)(lds + (bufoff) + ldsw + _i * 8192), 16, 0, 0); } while (0)
; #define PG8_LDA(dst, b, h) do { _Pragma("unroll") for (int m = 0; m < 4; ++m) _Pragma("unroll") for (int k = 0; k < 2; ++k) dst[m][k] = *(const PG8_LAS bf16x8*)(lds + PG8_SA(b, h) + aoff + m * 2048 + k * 1024); } while (0)
; #define PG8_LDB(dst, b, h) do { _Pragma("unroll") for (int n = 0; n < 2; ++n) _Pragma("unroll") for (int k = 0; k < 2; ++k) dst[n][k] = *(const PG8_LAS bf16x8*)(lds + PG8_SB(b, h) + boff + n * 2048 + k * 1024); } while (0)
; #define PG8_MMA(ai, bj, At, Bt) do { __builtin_amdgcn_s_setprio(1); _Pragma("unroll") for (int m = 0; m < 4; ++m) _Pragma("unroll") for (int n = 0; n < 2; ++n) _Pragma("unroll") for (int k = 0; k < 2; ++k) \
;         acc[ai][bj][m][n] = __builtin_amdgcn_mfma_f32_16x16x32_bf16(Bt[n][k], At[m][k], acc[ai][bj][m][n], 0, 0, 0); __builtin_amdgcn_s_setprio(0); } while (0)
; #define PG8_WAIT_V(n) asm volatile("s_waitcnt vmcnt(" #n ")" ::: "memory")
; #define PG8_WAIT_L(n) asm volatile("s_waitcnt lgkmcnt(" #n ")" ::: "memory")
; #define PG8_BAR __builtin_amdgcn_s_barrier()
; #define PG8_SCHED __builtin_amdgcn_sched_barrier(0)
;     __host__ __device__ bool next(int i, Unit& u) const {
;         const long L = (long)i * G + c; if (L >= nwg) return false;
;         int wgid = (int)L; { const int q = nwg / NXCD, r = nwg % NXCD, xcd = wgid % NXCD, off = wgid / NXCD; wgid = (xcd < r ? xcd * (q + 1) : r * (q + 1) + (xcd - r) * q) + off; }
;         const int nig = WGM * nN, gid = wgid / nig, fm = gid * WGM, gsz = (nM - fm) < WGM ? (nM - fm) : WGM;
;         u.pm = fm + ((wgid % nig) % gsz); u.pn = (wgid % nig) / gsz; u.k0 = 0; u.len = nt; u.kind = 0; return true;
; template <class Epi, class Sched, bool ALIGN_EPI = false, bool SP2 = false>
; __device__ __forceinline__ void gemm_phase(PG8_LAS unsigned char* lds, const Gemm g, const Sched& S, const Epi& E, const int wave_s) {
;     ...
;             PG8_LDB(B0, 0, 0); PG8_LDB(B1, 0, 1); PG8_SCHED; PG8_LDA(At, 0, 0); PG8_STAGE(PG8_SA(1, 1), a1 + hstep, voffA);
;             PG8_WAIT_V(8); PG8_WAIT_L(0); PG8_BAR; PG8_MMA(0, 0, At, B0); PG8_MMA(0, 1, At, B1); PG8_BAR; PG8_SCHED;
.LBB0_516:
	s_add_u32 s24, s24, 0x40080
	s_addc_u32 s25, s25, 0
	s_add_u32 s48, s2, 0x100
	s_addc_u32 s49, s3, 0
	s_mov_b32 s50, -2
	s_add_u32 s2, s24, 0xfffc0080
	s_addc_u32 s3, s25, -1
	s_add_i32 s51, 0, 0x10000
	s_cmp_eq_u32 s50, 12
	s_cselect_b32 s27, s19, s3
	s_cselect_b32 s26, s46, s2
	v_add_u32_e32 v144, s51, v147
	s_cselect_b32 s3, s17, s49
	s_cselect_b32 s2, s47, s48
	s_add_i32 s54, 0, 0x14000
	ds_read_b128 v[140:143], v144
	ds_read_b128 v[150:153], v144 offset:1024
	ds_read_b128 v[154:157], v144 offset:2048
	ds_read_b128 v[158:161], v144 offset:3072
	v_add_u32_e32 v144, s54, v147
	ds_read_b128 v[174:177], v144
	ds_read_b128 v[178:181], v144 offset:1024
	ds_read_b128 v[182:185], v144 offset:2048
	ds_read_b128 v[186:189], v144 offset:3072
	s_add_i32 m0, s35, 0xc000
	ds_read_b128 v[190:193], v148
	ds_read_b128 v[210:213], v148 offset:1024
	ds_read_b128 v[214:217], v148 offset:2048
	ds_read_b128 v[218:221], v148 offset:3072
	ds_read_b128 v[222:225], v148 offset:4096
	ds_read_b128 v[226:229], v148 offset:5120
	ds_read_b128 v[230:233], v148 offset:6144
	ds_read_b128 v[234:237], v148 offset:7168
	global_load_lds_dwordx4 v136, s[24:25]
	s_add_i32 m0, s35, 0xe000
	s_nop 0
	global_load_lds_dwordx4 v138, s[24:25]
	s_add_i32 s43, s43, 1
	s_mul_i32 s6, s43, s80
	s_mul_hi_u32 s7, s43, s93
	s_add_i32 s7, s7, s6
	s_mul_i32 s6, s43, s93
	s_add_u32 s20, s6, s64
	s_addc_u32 s21, s7, s65
	v_cmp_gt_i64_e32 vcc, s[20:21], v[168:169]
	v_cmp_lt_i64_e64 s[6:7], s[20:21], v[166:167]
	s_cbranch_vccnz .Lgum_522
	s_ashr_i32 s16, s20, 31
	s_lshr_b32 s16, s16, 29
	s_add_i32 s18, s20, s16
	s_and_b32 s16, s18, -8
	s_sub_i32 s19, s20, s16
	s_cmp_gt_i32 s19, 5
	s_mov_b64 s[16:17], -1
	s_cbranch_scc0 .Lgum_519
	s_mul_i32 s16, s19, 0xbd
	s_add_i32 s20, s16, 6
	s_mov_b64 s[16:17], 0

; #define PG8_STAGE(bufoff, gbase, voff) do { _Pragma("unroll") for (int _i = 0; _i < 2; ++_i) \
;         __builtin_amdgcn_global_load_lds((const unsigned*)((const char*)(gbase) + (voff)[_i]), (PG8_LAS unsigned*)(lds + (bufoff) + ldsw + _i * 8192), 16, 0, 0); } while (0)
; #define PG8_LDA(dst, b, h) do { _Pragma("unroll") for (int m = 0; m < 4; ++m) _Pragma("unroll") for (int k = 0; k < 2; ++k) dst[m][k] = *(const PG8_LAS bf16x8*)(lds + PG8_SA(b, h) + aoff + m * 2048 + k * 1024); } while (0)
; #define PG8_LDB(dst, b, h) do { _Pragma("unroll") for (int n = 0; n < 2; ++n) _Pragma("unroll") for (int k = 0; k < 2; ++k) dst[n][k] = *(const PG8_LAS bf16x8*)(lds + PG8_SB(b, h) + boff + n * 2048 + k * 1024); } while (0)
; #define PG8_WAIT_V(n) asm volatile("s_waitcnt vmcnt(" #n ")" ::: "memory")
; #define PG8_WAIT_L(n) asm volatile("s_waitcnt lgkmcnt(" #n ")" ::: "memory")
; template <class Epi, class Sched, bool ALIGN_EPI = false, bool SP2 = false>
; __device__ __forceinline__ void gemm_phase(PG8_LAS unsigned char* lds, const Gemm g, const Sched& S, const Epi& E, const int wave_s) {
;     ...
;         const bool has_next = S.next(ui + 1, nxt);
;         const char* nA = has_next ? (const char*)g.A + (size_t)nxt.pm * tstep + (size_t)nxt.k0 * kstep : cA; const char* nB = has_next ? (const char*)g.Bt + (size_t)nxt.pn * tstep + (size_t)nxt.k0 * kstep : cB;
;         const int clen = cur.len;
;         for (int t = 0; t < clen; t += 2) {
;             const bool last = (t == clen - 2);
;             const char* a1 = cA + (size_t)(t + 1) * kstep;
;             const char* a2 = last ? nA : cA + (size_t)(t + 2) * kstep; const char* b2 = last ? nB : cB + (size_t)(t + 2) * kstep;
;             const char* a3 = a2 + kstep; const char* b3 = b2 + kstep;
;             if (last && has_next) S.a_ready(nxt);
;             if constexpr (SP2) {
;             PG8_LDB(B0, 0, 0); PG8_LDB(B1, 0, 1); PG8_SCHED; PG8_LDA(At, 0, 0); PG8_STAGE(PG8_SA(1, 1), a1 + hstep, voffA);
;             PG8_WAIT_V(8); PG8_WAIT_L(0); PG8_BAR; PG8_MMA(0, 0, At, B0); PG8_MMA(0, 1, At, B1); PG8_BAR; PG8_SCHED;
;             PG8_LDA(At, 0, 1); PG8_STAGE(PG8_SB(0, 0), b2, voffB); PG8_STAGE(PG8_SB(0, 1), b2 + hstep, voffB); PG8_STAGE(PG8_SA(0, 0), a2, voffA);
;             PG8_WAIT_V(8); PG8_WAIT_L(0); PG8_BAR; PG8_MMA(1, 0, At, B0); PG8_MMA(1, 1, At, B1); PG8_BAR; PG8_SCHED;
.Lgum_522:
	s_ashr_i32 s19, s18, 31
	s_lshl_b64 s[20:21], s[18:19], 19
	s_add_u32 s20, s28, s20
	s_addc_u32 s21, s29, s21
	s_and_b64 s[22:23], s[6:7], exec
	s_cselect_b32 s19, s21, s25
	s_cselect_b32 s46, s20, s24
	s_ashr_i32 s17, s16, 31
	s_lshl_b64 s[22:23], s[16:17], 19
	s_add_u32 s22, s30, s22
	s_addc_u32 s23, s31, s23
	s_and_b64 s[100:101], s[6:7], exec
	s_cselect_b32 s17, s23, s49
	s_cselect_b32 s47, s22, s48
	s_waitcnt vmcnt(8)
	s_waitcnt lgkmcnt(0)
	s_barrier
	s_setprio 1
	s_waitcnt lgkmcnt(0)
	v_mfma_f32_16x16x32_bf16 v[124:127], v[140:143], v[190:193], 0
	v_mfma_f32_16x16x32_bf16 v[116:119], v[154:157], v[190:193], 0
	v_mfma_f32_16x16x32_bf16 v[108:111], v[140:143], v[214:217], 0
	v_mfma_f32_16x16x32_bf16 v[100:103], v[154:157], v[214:217], 0
	v_mfma_f32_16x16x32_bf16 v[92:95], v[140:143], v[222:225], 0
	v_mfma_f32_16x16x32_bf16 v[84:87], v[154:157], v[222:225], 0
	v_mfma_f32_16x16x32_bf16 v[76:79], v[140:143], v[230:233], 0
	v_mfma_f32_16x16x32_bf16 v[68:71], v[154:157], v[230:233], 0
	v_mfma_f32_16x16x32_bf16 v[124:127], v[150:153], v[210:213], v[124:127]
	v_mfma_f32_16x16x32_bf16 v[116:119], v[158:161], v[210:213], v[116:119]
	v_mfma_f32_16x16x32_bf16 v[108:111], v[150:153], v[218:221], v[108:111]
	v_mfma_f32_16x16x32_bf16 v[100:103], v[158:161], v[218:221], v[100:103]
	v_mfma_f32_16x16x32_bf16 v[92:95], v[150:153], v[226:229], v[92:95]
	v_mfma_f32_16x16x32_bf16 v[84:87], v[158:161], v[226:229], v[84:87]
	v_mfma_f32_16x16x32_bf16 v[76:79], v[150:153], v[234:237], v[76:79]
	v_mfma_f32_16x16x32_bf16 v[68:71], v[158:161], v[234:237], v[68:71]
	s_setprio 0
	s_setprio 1
	v_mfma_f32_16x16x32_bf16 v[120:123], v[174:177], v[190:193], 0
	v_mfma_f32_16x16x32_bf16 v[112:115], v[182:185], v[190:193], 0
	v_mfma_f32_16x16x32_bf16 v[104:107], v[174:177], v[214:217], 0
	v_mfma_f32_16x16x32_bf16 v[96:99], v[182:185], v[214:217], 0
	v_mfma_f32_16x16x32_bf16 v[88:91], v[174:177], v[222:225], 0
	v_mfma_f32_16x16x32_bf16 v[80:83], v[182:185], v[222:225], 0
	v_mfma_f32_16x16x32_bf16 v[72:75], v[174:177], v[230:233], 0
	v_mfma_f32_16x16x32_bf16 v[64:67], v[182:185], v[230:233], 0
	v_mfma_f32_16x16x32_bf16 v[120:123], v[178:181], v[210:213], v[120:123]
	v_mfma_f32_16x16x32_bf16 v[112:115], v[186:189], v[210:213], v[112:115]
	v_mfma_f32_16x16x32_bf16 v[104:107], v[178:181], v[218:221], v[104:107]
	v_mfma_f32_16x16x32_bf16 v[96:99], v[186:189], v[218:221], v[96:99]
	v_mfma_f32_16x16x32_bf16 v[88:91], v[178:181], v[226:229], v[88:91]
	v_mfma_f32_16x16x32_bf16 v[80:83], v[186:189], v[226:229], v[80:83]
	v_mfma_f32_16x16x32_bf16 v[72:75], v[178:181], v[234:237], v[72:75]
	v_mfma_f32_16x16x32_bf16 v[64:67], v[186:189], v[234:237], v[64:67]
	s_setprio 0
	s_barrier
	s_add_i32 s51, s51, s34
	s_mov_b32 m0, s51
	ds_read_b128 v[190:193], v148 offset:16384
	ds_read_b128 v[210:213], v148 offset:17408
	ds_read_b128 v[214:217], v148 offset:18432
	ds_read_b128 v[218:221], v148 offset:19456
	ds_read_b128 v[222:225], v148 offset:20480
	ds_read_b128 v[226:229], v148 offset:21504
	ds_read_b128 v[230:233], v148 offset:22528
	ds_read_b128 v[234:237], v148 offset:23552
	global_load_lds_dwordx4 v128, s[2:3]
	s_add_i32 m0, s51, 0x2000
	s_add_u32 s52, s2, 0x40000
	s_addc_u32 s53, s3, 0
	s_add_i32 s51, s54, s34
	global_load_lds_dwordx4 v130, s[2:3]
	s_mov_b32 m0, s51
	s_nop 0
	global_load_lds_dwordx4 v128, s[52:53]
	s_add_i32 m0, s51, 0x2000
	s_nop 0
	global_load_lds_dwordx4 v130, s[52:53]
	s_mov_b32 m0, s35
	s_nop 0
	global_load_lds_dwordx4 v134, s[26:27]
	s_mov_b32 m0, s36
	s_nop 0
	global_load_lds_dwordx4 v132, s[26:27]
	s_mov_b64 s[100:101], s[26:27]
	s_waitcnt vmcnt(8)
	s_waitcnt lgkmcnt(0)
	s_barrier
	s_setprio 1
	s_waitcnt lgkmcnt(0)
	v_mfma_f32_16x16x32_bf16 v[60:63], v[140:143], v[190:193], 0
	v_mfma_f32_16x16x32_bf16 v[52:55], v[154:157], v[190:193], 0
	v_mfma_f32_16x16x32_bf16 v[44:47], v[140:143], v[214:217], 0
	v_mfma_f32_16x16x32_bf16 v[36:39], v[154:157], v[214:217], 0
	v_mfma_f32_16x16x32_bf16 v[28:31], v[140:143], v[222:225], 0
	v_mfma_f32_16x16x32_bf16 v[20:23], v[154:157], v[222:225], 0
	v_mfma_f32_16x16x32_bf16 v[12:15], v[140:143], v[230:233], 0
	v_mfma_f32_16x16x32_bf16 v[4:7], v[154:157], v[230:233], 0
	v_mfma_f32_16x16x32_bf16 v[60:63], v[150:153], v[210:213], v[60:63]
	v_mfma_f32_16x16x32_bf16 v[52:55], v[158:161], v[210:213], v[52:55]
	v_mfma_f32_16x16x32_bf16 v[44:47], v[150:153], v[218:221], v[44:47]
	v_mfma_f32_16x16x32_bf16 v[36:39], v[158:161], v[218:221], v[36:39]
	v_mfma_f32_16x16x32_bf16 v[28:31], v[150:153], v[226:229], v[28:31]
	v_mfma_f32_16x16x32_bf16 v[20:23], v[158:161], v[226:229], v[20:23]
	v_mfma_f32_16x16x32_bf16 v[12:15], v[150:153], v[234:237], v[12:15]
	v_mfma_f32_16x16x32_bf16 v[4:7], v[158:161], v[234:237], v[4:7]
	s_setprio 0
	s_setprio 1
	v_mfma_f32_16x16x32_bf16 v[56:59], v[174:177], v[190:193], 0
	v_mfma_f32_16x16x32_bf16 v[48:51], v[182:185], v[190:193], 0
	v_mfma_f32_16x16x32_bf16 v[40:43], v[174:177], v[214:217], 0
	v_mfma_f32_16x16x32_bf16 v[32:35], v[182:185], v[214:217], 0
	v_mfma_f32_16x16x32_bf16 v[24:27], v[174:177], v[222:225], 0
	v_mfma_f32_16x16x32_bf16 v[16:19], v[182:185], v[222:225], 0
	v_mfma_f32_16x16x32_bf16 v[8:11], v[174:177], v[230:233], 0
	v_mfma_f32_16x16x32_bf16 v[0:3], v[182:185], v[230:233], 0
	v_mfma_f32_16x16x32_bf16 v[56:59], v[178:181], v[210:213], v[56:59]
	v_mfma_f32_16x16x32_bf16 v[48:51], v[186:189], v[210:213], v[48:51]
	v_mfma_f32_16x16x32_bf16 v[40:43], v[178:181], v[218:221], v[40:43]
	v_mfma_f32_16x16x32_bf16 v[32:35], v[186:189], v[218:221], v[32:35]
	v_mfma_f32_16x16x32_bf16 v[24:27], v[178:181], v[226:229], v[24:27]
	v_mfma_f32_16x16x32_bf16 v[16:19], v[186:189], v[226:229], v[16:19]
	v_mfma_f32_16x16x32_bf16 v[8:11], v[178:181], v[234:237], v[8:11]
	v_mfma_f32_16x16x32_bf16 v[0:3], v[186:189], v[234:237], v[0:3]
	s_setprio 0
	s_barrier
	s_branch .Lpeel1_seg3
; #define PG8_STAGE(bufoff, gbase, voff) do { _Pragma("unroll") for (int _i = 0; _i < 2; ++_i) \
;         __builtin_amdgcn_global_load_lds((const unsigned*)((const char*)(gbase) + (voff)[_i]), (PG8_LAS unsigned*)(lds + (bufoff) + ldsw + _i * 8192), 16, 0, 0); } while (0)
; #define PG8_LDA(dst, b, h) do { _Pragma("unroll") for (int m = 0; m < 4; ++m) _Pragma("unroll") for (int k = 0; k < 2; ++k) dst[m][k] = *(const PG8_LAS bf16x8*)(lds + PG8_SA(b, h) + aoff + m * 2048 + k * 1024); } while (0)
; #define PG8_LDB(dst, b, h) do { _Pragma("unroll") for (int n = 0; n < 2; ++n) _Pragma("unroll") for (int k = 0; k < 2; ++k) dst[n][k] = *(const PG8_LAS bf16x8*)(lds + PG8_SB(b, h) + boff + n * 2048 + k * 1024); } while (0)
; #define PG8_MMA(ai, bj, At, Bt) do { __builtin_amdgcn_s_setprio(1); _Pragma("unroll") for (int m = 0; m < 4; ++m) _Pragma("unroll") for (int n = 0; n < 2; ++n) _Pragma("unroll") for (int k = 0; k < 2; ++k) \
;         acc[ai][bj][m][n] = __builtin_amdgcn_mfma_f32_16x16x32_bf16(Bt[n][k], At[m][k], acc[ai][bj][m][n], 0, 0, 0); __builtin_amdgcn_s_setprio(0); } while (0)
; #define PG8_WAIT_V(n) asm volatile("s_waitcnt vmcnt(" #n ")" ::: "memory")
; #define PG8_WAIT_L(n) asm volatile("s_waitcnt lgkmcnt(" #n ")" ::: "memory")
; #define PG8_BAR __builtin_amdgcn_s_barrier()
; #define PG8_SCHED __builtin_amdgcn_sched_barrier(0)
; template <class Epi, class Sched, bool ALIGN_EPI = false, bool SP2 = false>
; __device__ __forceinline__ void gemm_phase(PG8_LAS unsigned char* lds, const Gemm g, const Sched& S, const Epi& E, const int wave_s) {
;     ...
;             PG8_LDB(B0, 0, 0); PG8_LDB(B1, 0, 1); PG8_SCHED; PG8_LDA(At, 0, 0); PG8_STAGE(PG8_SA(1, 1), a1 + hstep, voffA);
;             PG8_WAIT_V(8); PG8_WAIT_L(0); PG8_BAR; PG8_MMA(0, 0, At, B0); PG8_MMA(0, 1, At, B1); PG8_BAR; PG8_SCHED;
;             PG8_LDA(At, 0, 1); PG8_STAGE(PG8_SB(0, 0), b2, voffB); PG8_STAGE(PG8_SB(0, 1), b2 + hstep, voffB); PG8_STAGE(PG8_SA(0, 0), a2, voffA);
;             PG8_WAIT_V(8); PG8_WAIT_L(0); PG8_BAR; PG8_MMA(1, 0, At, B0); PG8_MMA(1, 1, At, B1); PG8_BAR; PG8_SCHED;
.LBB0_523:
	s_add_u32 s2, s24, 0xfffc0080
	s_addc_u32 s3, s25, -1
	s_add_i32 s51, 0, 0x10000
	s_cmp_eq_u32 s50, 12
	s_cselect_b32 s27, s19, s3
	s_cselect_b32 s26, s46, s2
	v_add_u32_e32 v144, s51, v147
	s_cselect_b32 s3, s17, s49
	s_cselect_b32 s2, s47, s48
	s_add_i32 s54, 0, 0x14000
	ds_read_b128 v[140:143], v144
	ds_read_b128 v[150:153], v144 offset:1024
	ds_read_b128 v[154:157], v144 offset:2048
	ds_read_b128 v[158:161], v144 offset:3072
	v_add_u32_e32 v144, s54, v147
	ds_read_b128 v[174:177], v144
	ds_read_b128 v[178:181], v144 offset:1024
	ds_read_b128 v[182:185], v144 offset:2048
	ds_read_b128 v[186:189], v144 offset:3072
	s_add_i32 m0, s35, 0xc000
	ds_read_b128 v[190:193], v148
	ds_read_b128 v[210:213], v148 offset:1024
	ds_read_b128 v[214:217], v148 offset:2048
	ds_read_b128 v[218:221], v148 offset:3072
	ds_read_b128 v[222:225], v148 offset:4096
	ds_read_b128 v[226:229], v148 offset:5120
	ds_read_b128 v[230:233], v148 offset:6144
	ds_read_b128 v[234:237], v148 offset:7168
	global_load_lds_dwordx4 v136, s[24:25]
	s_add_i32 m0, s35, 0xe000
	s_nop 0
	global_load_lds_dwordx4 v138, s[24:25]
	s_waitcnt vmcnt(8)
	s_waitcnt lgkmcnt(0)
	s_barrier
	s_setprio 1
	s_waitcnt lgkmcnt(0)
	v_mfma_f32_16x16x32_bf16 v[124:127], v[140:143], v[190:193], v[124:127]
	v_mfma_f32_16x16x32_bf16 v[116:119], v[154:157], v[190:193], v[116:119]
	v_mfma_f32_16x16x32_bf16 v[108:111], v[140:143], v[214:217], v[108:111]
	v_mfma_f32_16x16x32_bf16 v[100:103], v[154:157], v[214:217], v[100:103]
	v_mfma_f32_16x16x32_bf16 v[92:95], v[140:143], v[222:225], v[92:95]
	v_mfma_f32_16x16x32_bf16 v[84:87], v[154:157], v[222:225], v[84:87]
	v_mfma_f32_16x16x32_bf16 v[76:79], v[140:143], v[230:233], v[76:79]
	v_mfma_f32_16x16x32_bf16 v[68:71], v[154:157], v[230:233], v[68:71]
	v_mfma_f32_16x16x32_bf16 v[124:127], v[150:153], v[210:213], v[124:127]
	v_mfma_f32_16x16x32_bf16 v[116:119], v[158:161], v[210:213], v[116:119]
	v_mfma_f32_16x16x32_bf16 v[108:111], v[150:153], v[218:221], v[108:111]
	v_mfma_f32_16x16x32_bf16 v[100:103], v[158:161], v[218:221], v[100:103]
	v_mfma_f32_16x16x32_bf16 v[92:95], v[150:153], v[226:229], v[92:95]
	v_mfma_f32_16x16x32_bf16 v[84:87], v[158:161], v[226:229], v[84:87]
	v_mfma_f32_16x16x32_bf16 v[76:79], v[150:153], v[234:237], v[76:79]
	v_mfma_f32_16x16x32_bf16 v[68:71], v[158:161], v[234:237], v[68:71]
	s_setprio 0
	s_setprio 1
	v_mfma_f32_16x16x32_bf16 v[120:123], v[174:177], v[190:193], v[120:123]
	v_mfma_f32_16x16x32_bf16 v[112:115], v[182:185], v[190:193], v[112:115]
	v_mfma_f32_16x16x32_bf16 v[104:107], v[174:177], v[214:217], v[104:107]
	v_mfma_f32_16x16x32_bf16 v[96:99], v[182:185], v[214:217], v[96:99]
	v_mfma_f32_16x16x32_bf16 v[88:91], v[174:177], v[222:225], v[88:91]
	v_mfma_f32_16x16x32_bf16 v[80:83], v[182:185], v[222:225], v[80:83]
	v_mfma_f32_16x16x32_bf16 v[72:75], v[174:177], v[230:233], v[72:75]
	v_mfma_f32_16x16x32_bf16 v[64:67], v[182:185], v[230:233], v[64:67]
	v_mfma_f32_16x16x32_bf16 v[120:123], v[178:181], v[210:213], v[120:123]
	v_mfma_f32_16x16x32_bf16 v[112:115], v[186:189], v[210:213], v[112:115]
	v_mfma_f32_16x16x32_bf16 v[104:107], v[178:181], v[218:221], v[104:107]
	v_mfma_f32_16x16x32_bf16 v[96:99], v[186:189], v[218:221], v[96:99]
	v_mfma_f32_16x16x32_bf16 v[88:91], v[178:181], v[226:229], v[88:91]
	v_mfma_f32_16x16x32_bf16 v[80:83], v[186:189], v[226:229], v[80:83]
	v_mfma_f32_16x16x32_bf16 v[72:75], v[178:181], v[234:237], v[72:75]
	v_mfma_f32_16x16x32_bf16 v[64:67], v[186:189], v[234:237], v[64:67]
	s_setprio 0
	s_barrier
	s_add_i32 s51, s51, s34
	s_mov_b32 m0, s51
	ds_read_b128 v[190:193], v148 offset:16384
	ds_read_b128 v[210:213], v148 offset:17408
	ds_read_b128 v[214:217], v148 offset:18432
	ds_read_b128 v[218:221], v148 offset:19456
	ds_read_b128 v[222:225], v148 offset:20480
	ds_read_b128 v[226:229], v148 offset:21504
	ds_read_b128 v[230:233], v148 offset:22528
	ds_read_b128 v[234:237], v148 offset:23552
	global_load_lds_dwordx4 v128, s[2:3]
	s_add_i32 m0, s51, 0x2000
	s_add_u32 s52, s2, 0x40000
	s_addc_u32 s53, s3, 0
	s_add_i32 s51, s54, s34
	global_load_lds_dwordx4 v130, s[2:3]
	s_mov_b32 m0, s51
	s_nop 0
	global_load_lds_dwordx4 v128, s[52:53]
	s_add_i32 m0, s51, 0x2000
	s_nop 0
	global_load_lds_dwordx4 v130, s[52:53]
	s_mov_b32 m0, s35
	s_nop 0
	global_load_lds_dwordx4 v134, s[26:27]
	s_mov_b32 m0, s36
	s_nop 0
	global_load_lds_dwordx4 v132, s[26:27]
	s_mov_b64 s[100:101], s[26:27]
	s_waitcnt vmcnt(8)
	s_waitcnt lgkmcnt(0)
	s_barrier
	s_setprio 1
	s_waitcnt lgkmcnt(0)
	v_mfma_f32_16x16x32_bf16 v[60:63], v[140:143], v[190:193], v[60:63]
	v_mfma_f32_16x16x32_bf16 v[52:55], v[154:157], v[190:193], v[52:55]
	v_mfma_f32_16x16x32_bf16 v[44:47], v[140:143], v[214:217], v[44:47]
	v_mfma_f32_16x16x32_bf16 v[36:39], v[154:157], v[214:217], v[36:39]
	v_mfma_f32_16x16x32_bf16 v[28:31], v[140:143], v[222:225], v[28:31]
	v_mfma_f32_16x16x32_bf16 v[20:23], v[154:157], v[222:225], v[20:23]
	v_mfma_f32_16x16x32_bf16 v[12:15], v[140:143], v[230:233], v[12:15]
	v_mfma_f32_16x16x32_bf16 v[4:7], v[154:157], v[230:233], v[4:7]
	v_mfma_f32_16x16x32_bf16 v[60:63], v[150:153], v[210:213], v[60:63]
	v_mfma_f32_16x16x32_bf16 v[52:55], v[158:161], v[210:213], v[52:55]
	v_mfma_f32_16x16x32_bf16 v[44:47], v[150:153], v[218:221], v[44:47]
	v_mfma_f32_16x16x32_bf16 v[36:39], v[158:161], v[218:221], v[36:39]
	v_mfma_f32_16x16x32_bf16 v[28:31], v[150:153], v[226:229], v[28:31]
	v_mfma_f32_16x16x32_bf16 v[20:23], v[158:161], v[226:229], v[20:23]
	v_mfma_f32_16x16x32_bf16 v[12:15], v[150:153], v[234:237], v[12:15]
	v_mfma_f32_16x16x32_bf16 v[4:7], v[158:161], v[234:237], v[4:7]
	s_setprio 0
	s_setprio 1
	v_mfma_f32_16x16x32_bf16 v[56:59], v[174:177], v[190:193], v[56:59]
	v_mfma_f32_16x16x32_bf16 v[48:51], v[182:185], v[190:193], v[48:51]
	v_mfma_f32_16x16x32_bf16 v[40:43], v[174:177], v[214:217], v[40:43]
	v_mfma_f32_16x16x32_bf16 v[32:35], v[182:185], v[214:217], v[32:35]
	v_mfma_f32_16x16x32_bf16 v[24:27], v[174:177], v[222:225], v[24:27]
	v_mfma_f32_16x16x32_bf16 v[16:19], v[182:185], v[222:225], v[16:19]
	v_mfma_f32_16x16x32_bf16 v[8:11], v[174:177], v[230:233], v[8:11]
	v_mfma_f32_16x16x32_bf16 v[0:3], v[182:185], v[230:233], v[0:3]
	v_mfma_f32_16x16x32_bf16 v[56:59], v[178:181], v[210:213], v[56:59]
	v_mfma_f32_16x16x32_bf16 v[48:51], v[186:189], v[210:213], v[48:51]
	v_mfma_f32_16x16x32_bf16 v[40:43], v[178:181], v[218:221], v[40:43]
	v_mfma_f32_16x16x32_bf16 v[32:35], v[186:189], v[218:221], v[32:35]
	v_mfma_f32_16x16x32_bf16 v[24:27], v[178:181], v[226:229], v[24:27]
	v_mfma_f32_16x16x32_bf16 v[16:19], v[186:189], v[226:229], v[16:19]
	v_mfma_f32_16x16x32_bf16 v[8:11], v[178:181], v[234:237], v[8:11]
	v_mfma_f32_16x16x32_bf16 v[0:3], v[186:189], v[234:237], v[0:3]
	s_setprio 0
	s_barrier
; #define PG8_STAGE(bufoff, gbase, voff) do { _Pragma("unroll") for (int _i = 0; _i < 2; ++_i) \
;         __builtin_amdgcn_global_load_lds((const unsigned*)((const char*)(gbase) + (voff)[_i]), (PG8_LAS unsigned*)(lds + (bufoff) + ldsw + _i * 8192), 16, 0, 0); } while (0)
; #define PG8_LDA(dst, b, h) do { _Pragma("unroll") for (int m = 0; m < 4; ++m) _Pragma("unroll") for (int k = 0; k < 2; ++k) dst[m][k] = *(const PG8_LAS bf16x8*)(lds + PG8_SA(b, h) + aoff + m * 2048 + k * 1024); } while (0)
; #define PG8_LDB(dst, b, h) do { _Pragma("unroll") for (int n = 0; n < 2; ++n) _Pragma("unroll") for (int k = 0; k < 2; ++k) dst[n][k] = *(const PG8_LAS bf16x8*)(lds + PG8_SB(b, h) + boff + n * 2048 + k * 1024); } while (0)
; #define PG8_MMA(ai, bj, At, Bt) do { __builtin_amdgcn_s_setprio(1); _Pragma("unroll") for (int m = 0; m < 4; ++m) _Pragma("unroll") for (int n = 0; n < 2; ++n) _Pragma("unroll") for (int k = 0; k < 2; ++k) \
;         acc[ai][bj][m][n] = __builtin_amdgcn_mfma_f32_16x16x32_bf16(Bt[n][k], At[m][k], acc[ai][bj][m][n], 0, 0, 0); __builtin_amdgcn_s_setprio(0); } while (0)
; #define PG8_WAIT_V(n) asm volatile("s_waitcnt vmcnt(" #n ")" ::: "memory")
; #define PG8_WAIT_L(n) asm volatile("s_waitcnt lgkmcnt(" #n ")" ::: "memory")
; #define PG8_BAR __builtin_amdgcn_s_barrier()
; #define PG8_SCHED __builtin_amdgcn_sched_barrier(0)
; template <class Epi, class Sched, bool ALIGN_EPI = false, bool SP2 = false>
; __device__ __forceinline__ void gemm_phase(PG8_LAS unsigned char* lds, const Gemm g, const Sched& S, const Epi& E, const int wave_s) {
;     ...
;             PG8_LDB(B0, 1, 0); PG8_LDB(B1, 1, 1); PG8_SCHED; PG8_LDA(At, 1, 0); PG8_STAGE(PG8_SA(0, 1), a2 + hstep, voffA);
;             PG8_WAIT_V(8); PG8_WAIT_L(0); PG8_BAR; PG8_MMA(0, 0, At, B0); PG8_MMA(0, 1, At, B1); PG8_BAR; PG8_SCHED;
;             PG8_LDA(At, 1, 1); PG8_STAGE(PG8_SB(1, 0), b3, voffB); PG8_STAGE(PG8_SB(1, 1), b3 + hstep, voffB); PG8_STAGE(PG8_SA(1, 0), a3, voffA);
;             PG8_WAIT_V(8); PG8_WAIT_L(0); PG8_BAR; PG8_MMA(1, 0, At, B0); PG8_MMA(1, 1, At, B1); PG8_BAR; PG8_SCHED;
;     ...
;         }
;         if constexpr (ALIGN_EPI) { if (wr == 0) PG8_BAR; }
.Lpeel1_seg3:
	s_add_i32 s51, 0, 0x18000
	v_add_u32_e32 v144, s51, v147
	s_add_i32 s52, 0, 0x1c000
	ds_read_b128 v[140:143], v144
	ds_read_b128 v[150:153], v144 offset:1024
	ds_read_b128 v[154:157], v144 offset:2048
	ds_read_b128 v[158:161], v144 offset:3072
	v_add_u32_e32 v144, s52, v147
	ds_read_b128 v[174:177], v144
	ds_read_b128 v[178:181], v144 offset:1024
	ds_read_b128 v[182:185], v144 offset:2048
	ds_read_b128 v[186:189], v144 offset:3072
	s_add_u32 s26, s26, 0x40000
	s_addc_u32 s27, s27, 0
	s_mov_b32 m0, s37
	ds_read_b128 v[190:193], v148 offset:32768
	ds_read_b128 v[210:213], v148 offset:33792
	ds_read_b128 v[214:217], v148 offset:34816
	ds_read_b128 v[218:221], v148 offset:35840
	ds_read_b128 v[222:225], v148 offset:36864
	ds_read_b128 v[226:229], v148 offset:37888
	ds_read_b128 v[230:233], v148 offset:38912
	ds_read_b128 v[234:237], v148 offset:39936
	global_load_lds_dwordx4 v134, s[26:27]
	s_mov_b32 m0, s38
	s_nop 0
	global_load_lds_dwordx4 v132, s[26:27]
	s_waitcnt vmcnt(8)
	s_waitcnt lgkmcnt(0)
	s_barrier
	s_setprio 1
	s_waitcnt lgkmcnt(0)
	v_mfma_f32_16x16x32_bf16 v[124:127], v[140:143], v[190:193], v[124:127]
	v_mfma_f32_16x16x32_bf16 v[116:119], v[154:157], v[190:193], v[116:119]
	v_mfma_f32_16x16x32_bf16 v[108:111], v[140:143], v[214:217], v[108:111]
	v_mfma_f32_16x16x32_bf16 v[100:103], v[154:157], v[214:217], v[100:103]
	v_mfma_f32_16x16x32_bf16 v[92:95], v[140:143], v[222:225], v[92:95]
	v_mfma_f32_16x16x32_bf16 v[84:87], v[154:157], v[222:225], v[84:87]
	v_mfma_f32_16x16x32_bf16 v[76:79], v[140:143], v[230:233], v[76:79]
	v_mfma_f32_16x16x32_bf16 v[68:71], v[154:157], v[230:233], v[68:71]
	v_mfma_f32_16x16x32_bf16 v[124:127], v[150:153], v[210:213], v[124:127]
	v_mfma_f32_16x16x32_bf16 v[116:119], v[158:161], v[210:213], v[116:119]
	v_mfma_f32_16x16x32_bf16 v[108:111], v[150:153], v[218:221], v[108:111]
	v_mfma_f32_16x16x32_bf16 v[100:103], v[158:161], v[218:221], v[100:103]
	v_mfma_f32_16x16x32_bf16 v[92:95], v[150:153], v[226:229], v[92:95]
	v_mfma_f32_16x16x32_bf16 v[84:87], v[158:161], v[226:229], v[84:87]
	v_mfma_f32_16x16x32_bf16 v[76:79], v[150:153], v[234:237], v[76:79]
	v_mfma_f32_16x16x32_bf16 v[68:71], v[158:161], v[234:237], v[68:71]
	s_setprio 0
	s_setprio 1
	v_mfma_f32_16x16x32_bf16 v[120:123], v[174:177], v[190:193], v[120:123]
	v_mfma_f32_16x16x32_bf16 v[112:115], v[182:185], v[190:193], v[112:115]
	v_mfma_f32_16x16x32_bf16 v[104:107], v[174:177], v[214:217], v[104:107]
	v_mfma_f32_16x16x32_bf16 v[96:99], v[182:185], v[214:217], v[96:99]
	v_mfma_f32_16x16x32_bf16 v[88:91], v[174:177], v[222:225], v[88:91]
	v_mfma_f32_16x16x32_bf16 v[80:83], v[182:185], v[222:225], v[80:83]
	v_mfma_f32_16x16x32_bf16 v[72:75], v[174:177], v[230:233], v[72:75]
	v_mfma_f32_16x16x32_bf16 v[64:67], v[182:185], v[230:233], v[64:67]
	v_mfma_f32_16x16x32_bf16 v[120:123], v[178:181], v[210:213], v[120:123]
	v_mfma_f32_16x16x32_bf16 v[112:115], v[186:189], v[210:213], v[112:115]
	v_mfma_f32_16x16x32_bf16 v[104:107], v[178:181], v[218:221], v[104:107]
	v_mfma_f32_16x16x32_bf16 v[96:99], v[186:189], v[218:221], v[96:99]
	v_mfma_f32_16x16x32_bf16 v[88:91], v[178:181], v[226:229], v[88:91]
	v_mfma_f32_16x16x32_bf16 v[80:83], v[186:189], v[226:229], v[80:83]
	v_mfma_f32_16x16x32_bf16 v[72:75], v[178:181], v[234:237], v[72:75]
	v_mfma_f32_16x16x32_bf16 v[64:67], v[186:189], v[234:237], v[64:67]
	s_setprio 0
	s_barrier
	s_add_i32 s26, s51, s34
	s_add_i32 m0, s26, 0xffffff80
	ds_read_b128 v[190:193], v148 offset:49152
	ds_read_b128 v[210:213], v148 offset:50176
	ds_read_b128 v[214:217], v148 offset:51200
	ds_read_b128 v[218:221], v148 offset:52224
	ds_read_b128 v[222:225], v148 offset:53248
	ds_read_b128 v[226:229], v148 offset:54272
	ds_read_b128 v[230:233], v148 offset:55296
	ds_read_b128 v[234:237], v148 offset:56320
	global_load_lds_dwordx4 v128, s[2:3] offset:128
	s_add_i32 m0, s26, 0x1f80
	s_add_i32 s26, s52, s34
	global_load_lds_dwordx4 v130, s[2:3] offset:128
	s_add_u32 s2, s2, 0x40080
	s_addc_u32 s3, s3, 0
	s_mov_b32 m0, s26
	s_nop 0
	global_load_lds_dwordx4 v128, s[2:3]
	s_add_i32 m0, s26, 0x2000
	s_nop 0
	global_load_lds_dwordx4 v130, s[2:3]
	s_add_i32 m0, s41, 0xffffff80
	s_nop 0
	global_load_lds_dwordx4 v134, s[100:101] offset:128
	s_add_i32 m0, s42, 0xffffff80
	s_nop 0
	global_load_lds_dwordx4 v132, s[100:101] offset:128
	s_waitcnt vmcnt(8)
	s_waitcnt lgkmcnt(0)
	s_barrier
	s_setprio 1
	s_waitcnt lgkmcnt(0)
	v_mfma_f32_16x16x32_bf16 v[60:63], v[140:143], v[190:193], v[60:63]
	v_mfma_f32_16x16x32_bf16 v[52:55], v[154:157], v[190:193], v[52:55]
	v_mfma_f32_16x16x32_bf16 v[44:47], v[140:143], v[214:217], v[44:47]
	v_mfma_f32_16x16x32_bf16 v[36:39], v[154:157], v[214:217], v[36:39]
	v_mfma_f32_16x16x32_bf16 v[28:31], v[140:143], v[222:225], v[28:31]
	v_mfma_f32_16x16x32_bf16 v[20:23], v[154:157], v[222:225], v[20:23]
	v_mfma_f32_16x16x32_bf16 v[12:15], v[140:143], v[230:233], v[12:15]
	v_mfma_f32_16x16x32_bf16 v[4:7], v[154:157], v[230:233], v[4:7]
	v_mfma_f32_16x16x32_bf16 v[60:63], v[150:153], v[210:213], v[60:63]
	v_mfma_f32_16x16x32_bf16 v[52:55], v[158:161], v[210:213], v[52:55]
	v_mfma_f32_16x16x32_bf16 v[44:47], v[150:153], v[218:221], v[44:47]
	v_mfma_f32_16x16x32_bf16 v[36:39], v[158:161], v[218:221], v[36:39]
	v_mfma_f32_16x16x32_bf16 v[28:31], v[150:153], v[226:229], v[28:31]
	v_mfma_f32_16x16x32_bf16 v[20:23], v[158:161], v[226:229], v[20:23]
	v_mfma_f32_16x16x32_bf16 v[12:15], v[150:153], v[234:237], v[12:15]
	v_mfma_f32_16x16x32_bf16 v[4:7], v[158:161], v[234:237], v[4:7]
	s_setprio 0
	s_setprio 1
	v_mfma_f32_16x16x32_bf16 v[56:59], v[174:177], v[190:193], v[56:59]
	v_mfma_f32_16x16x32_bf16 v[48:51], v[182:185], v[190:193], v[48:51]
	v_mfma_f32_16x16x32_bf16 v[40:43], v[174:177], v[214:217], v[40:43]
	v_mfma_f32_16x16x32_bf16 v[32:35], v[182:185], v[214:217], v[32:35]
	v_mfma_f32_16x16x32_bf16 v[24:27], v[174:177], v[222:225], v[24:27]
	v_mfma_f32_16x16x32_bf16 v[16:19], v[182:185], v[222:225], v[16:19]
	v_mfma_f32_16x16x32_bf16 v[8:11], v[174:177], v[230:233], v[8:11]
	v_mfma_f32_16x16x32_bf16 v[0:3], v[182:185], v[230:233], v[0:3]
	v_mfma_f32_16x16x32_bf16 v[56:59], v[178:181], v[210:213], v[56:59]
	v_mfma_f32_16x16x32_bf16 v[48:51], v[186:189], v[210:213], v[48:51]
	v_mfma_f32_16x16x32_bf16 v[40:43], v[178:181], v[218:221], v[40:43]
	v_mfma_f32_16x16x32_bf16 v[32:35], v[186:189], v[218:221], v[32:35]
	v_mfma_f32_16x16x32_bf16 v[24:27], v[178:181], v[226:229], v[24:27]
	v_mfma_f32_16x16x32_bf16 v[16:19], v[186:189], v[226:229], v[16:19]
	v_mfma_f32_16x16x32_bf16 v[8:11], v[178:181], v[234:237], v[8:11]
	v_mfma_f32_16x16x32_bf16 v[0:3], v[186:189], v[234:237], v[0:3]
	s_setprio 0
	s_barrier
	s_add_i32 s50, s50, 2
	s_add_u32 s24, s24, 0x100
	s_addc_u32 s25, s25, 0
	s_add_u32 s48, s48, 0x100
	s_addc_u32 s49, s49, 0
	s_cmp_gt_u32 s50, 13
	s_cbranch_scc0 .LBB0_523
	s_and_b64 vcc, exec, s[14:15]
	s_cbranch_vccz .LBB0_526
	s_barrier
